# selected-branch interior tile software-pipelined inside the wave: exp of one 32-key half between the other half's QK MFMAs, exp of the second half between the first half's PV MFMAs
# speedup vs baseline: 1.0056x; 1.0056x over previous
; #define LAS __attribute__((address_space(3)))
; template <int BR>
; DI void attn_branch(const AttnCtx& c, unsigned long long tmask, const bf16_t* kbase, size_t kpitch, const bf16_t* vbase, size_t vpitch, f32x16 (&o)[2], float& lsum) {
;     ...
;         bool mine = true;
;         if (BR == 2) mine = (c.mymask >> jc) & 1ull;
;         const bool wave_on = (BR == 2 ? (__ballot(mine) != 0ull) : true) && !c.nocompute;
;         if (wave_on) {
;             const float sbias = (BR == 2 && !mine) ? -1e30f : 0.f;
;             bool interior;
;             if (BR <= 1) interior = jc * 64 + 64 <= c.ncvmin;
;             else if (BR == 2) interior = jc * 64 + 63 <= c.tw;
;             else interior = (jc * 64 + 63 <= c.tw) && (jc * 64 > c.tw + 31 - 512);
;             if (interior) {
;                 f32x16 s0, s1;
; #pragma unroll
;                 for (int i = 0; i < 16; ++i) { s0[i] = sbias; s1[i] = sbias; }
; #pragma unroll
;                 for (int st = 0; st < 4; ++st) {
;                     const bf16x8 kf0 = *(const LAS bf16x8*)(Ks + c.qi * 72 + 16 * st + 8 * c.hi), kf1 = *(const LAS bf16x8*)(Ks + (32 + c.qi) * 72 + 16 * st + 8 * c.hi);
;                     s0 = MFMA32(kf0, c.q[st], s0); s1 = MFMA32(kf1, c.q[st], s1);
;                 }
;                 float p0[16], p1[16];
; #pragma unroll
;                 for (int i = 0; i < 16; ++i) { p0[i] = __builtin_amdgcn_exp2f(s0[i]); p1[i] = __builtin_amdgcn_exp2f(s1[i]); }
;                 {
;                     float l0 = 0.f, l1 = 0.f;
; #pragma unroll
;                     for (int i = 0; i < 16; ++i) { l0 += p0[i]; l1 += p1[i]; }
;                     lsum += l0 + l1;
;                 }
;                 if (BR == 1) {
; #pragma unroll
;                     for (int gq = 0; gq < 4; ++gq) {
;                         const int jj = jc * 16 + gq * 2 + c.hi;
;                         __hip_atomic_fetch_add(c.impw + jj, (p0[4 * gq] + p0[4 * gq + 1]) + (p0[4 * gq + 2] + p0[4 * gq + 3]), __ATOMIC_RELAXED, __HIP_MEMORY_SCOPE_WORKGROUP);
;                         __hip_atomic_fetch_add(c.impw + jj + 1, p0[4 * gq + 3], __ATOMIC_RELAXED, __HIP_MEMORY_SCOPE_WORKGROUP);
;                     }
; #pragma unroll
;                     for (int gq = 0; gq < 4; ++gq) {
;                         const int jj = jc * 16 + 8 + gq * 2 + c.hi;
.LBB0_377:
	s_waitcnt lgkmcnt(0)
	s_barrier
	v_lshrrev_b64 v[64:65], s10, v[106:107]
	v_and_b32_e32 v64, 1, v64
	v_cmp_eq_u32_e64 s[0:1], 1, v64
	v_cmp_ne_u32_e32 vcc, 0, v64
	s_cbranch_vccz .LBB0_387
	s_lshl_b32 s15, s10, 6
	v_cndmask_b32_e64 v64, v193, 0, s[0:1]
	s_or_b32 s0, s15, 63
	v_cmp_le_i32_e32 vcc, s0, v171
	s_and_saveexec_b64 s[0:1], vcc
	s_xor_b64 s[0:1], exec, s[0:1]
	s_cbranch_execz .LBB0_380
	v_lshlrev_b32_e32 v80, 1, v170
	v_add3_u32 v109, s14, v185, v80
	ds_read_b128 v[212:215], v109
	ds_read_b128 v[216:219], v109 offset:4608
	ds_read_b128 v[220:223], v109 offset:32
	ds_read_b128 v[224:227], v109 offset:4640
	ds_read_b128 v[228:231], v109 offset:64
	ds_read_b128 v[232:235], v109 offset:4672
	ds_read_b128 v[236:239], v109 offset:96
	ds_read_b128 v[240:243], v109 offset:4704
	v_mov_b32_e32 v65, v64
	v_mov_b32_e32 v66, v64
	v_mov_b32_e32 v67, v64
	v_mov_b32_e32 v68, v64
	v_mov_b32_e32 v69, v64
	v_mov_b32_e32 v70, v64
	v_mov_b32_e32 v71, v64
	v_mov_b32_e32 v72, v64
	v_mov_b32_e32 v73, v64
	v_mov_b32_e32 v74, v64
	v_mov_b32_e32 v75, v64
	v_mov_b32_e32 v76, v64
	v_mov_b32_e32 v77, v64
	v_mov_b32_e32 v78, v64
	v_mov_b32_e32 v79, v64
	s_nop 0
	s_waitcnt lgkmcnt(7)
	v_mfma_f32_32x32x16_bf16 v[80:95], v[212:215], v[130:133], v[64:79]
	s_waitcnt lgkmcnt(5)
	v_mfma_f32_32x32x16_bf16 v[80:95], v[220:223], v[134:137], v[80:95]
	s_waitcnt lgkmcnt(3)
	v_mfma_f32_32x32x16_bf16 v[80:95], v[228:231], v[138:141], v[80:95]
	s_waitcnt lgkmcnt(1)
	v_mfma_f32_32x32x16_bf16 v[80:95], v[236:239], v[142:145], v[80:95]
	s_waitcnt lgkmcnt(0)
	v_mfma_f32_32x32x16_bf16 v[64:79], v[216:219], v[130:133], v[64:79]
	v_mfma_f32_32x32x16_bf16 v[64:79], v[224:227], v[134:137], v[64:79]
	s_nop 9
	v_exp_f32_e32 v80, v80
	v_exp_f32_e32 v81, v81
	v_exp_f32_e32 v82, v82
	v_mfma_f32_32x32x16_bf16 v[64:79], v[232:235], v[138:141], v[64:79]
	v_exp_f32_e32 v83, v83
	v_exp_f32_e32 v84, v84
	v_exp_f32_e32 v85, v85
	v_mfma_f32_32x32x16_bf16 v[64:79], v[240:243], v[142:145], v[64:79]
	v_add3_u32 v251, s14, v186, v170
	v_add_u32_e32 v255, 0x2000, v251
	v_add_u32_e32 v251, 0x3000, v251
	ds_read2_b64 v[212:215], v255 offset0:128 offset1:130
	ds_read2_b64 v[216:219], v251 offset0:160 offset1:162
	ds_read2_b64 v[220:223], v255 offset0:132 offset1:134
	ds_read2_b64 v[224:227], v251 offset0:164 offset1:166
	ds_read2_b64 v[228:231], v255 offset0:136 offset1:138
	ds_read2_b64 v[232:235], v251 offset0:168 offset1:170
	ds_read2_b64 v[236:239], v255 offset0:140 offset1:142
	ds_read2_b64 v[240:243], v251 offset0:172 offset1:174
	v_exp_f32_e32 v86, v86
	v_exp_f32_e32 v87, v87
	v_exp_f32_e32 v88, v88
	v_exp_f32_e32 v89, v89
	v_exp_f32_e32 v90, v90
	v_exp_f32_e32 v91, v91
	v_exp_f32_e32 v92, v92
	v_exp_f32_e32 v93, v93
	v_exp_f32_e32 v94, v94
	v_exp_f32_e32 v95, v95
	v_pk_add_f32 v[252:253], v[80:81], v[82:83]
	v_pk_add_f32 v[252:253], v[84:85], v[252:253]
	v_pk_add_f32 v[252:253], v[86:87], v[252:253]
	v_pk_add_f32 v[252:253], v[88:89], v[252:253]
	v_pk_add_f32 v[252:253], v[90:91], v[252:253]
	v_pk_add_f32 v[252:253], v[92:93], v[252:253]
	v_pk_add_f32 v[252:253], v[94:95], v[252:253]
	v_cvt_pk_bf16_f32 v116, v80, v81
	v_cvt_pk_bf16_f32 v117, v82, v83
	v_cvt_pk_bf16_f32 v118, v84, v85
	v_cvt_pk_bf16_f32 v119, v86, v87
	v_cvt_pk_bf16_f32 v120, v88, v89
	v_cvt_pk_bf16_f32 v121, v90, v91
	v_cvt_pk_bf16_f32 v122, v92, v93
	v_cvt_pk_bf16_f32 v123, v94, v95
	s_waitcnt lgkmcnt(0)
	v_mfma_f32_32x32x16_bf16 v[48:63], v[212:215], v[116:119], v[48:63]
	v_exp_f32_e32 v64, v64
	v_exp_f32_e32 v65, v65
	v_exp_f32_e32 v66, v66
	v_exp_f32_e32 v67, v67
	v_mfma_f32_32x32x16_bf16 v[32:47], v[216:219], v[116:119], v[32:47]
	v_exp_f32_e32 v68, v68
	v_exp_f32_e32 v69, v69
	v_exp_f32_e32 v70, v70
	v_exp_f32_e32 v71, v71
	v_mfma_f32_32x32x16_bf16 v[48:63], v[220:223], v[120:123], v[48:63]
	v_exp_f32_e32 v72, v72
	v_exp_f32_e32 v73, v73
	v_exp_f32_e32 v74, v74
	v_exp_f32_e32 v75, v75
	v_mfma_f32_32x32x16_bf16 v[32:47], v[224:227], v[120:123], v[32:47]
	v_exp_f32_e32 v76, v76
	v_exp_f32_e32 v77, v77
	v_exp_f32_e32 v78, v78
	v_exp_f32_e32 v79, v79
	v_pk_add_f32 v[252:253], v[64:65], v[252:253]
	v_pk_add_f32 v[252:253], v[66:67], v[252:253]
	v_pk_add_f32 v[252:253], v[68:69], v[252:253]
	v_pk_add_f32 v[252:253], v[70:71], v[252:253]
	v_pk_add_f32 v[252:253], v[72:73], v[252:253]
	v_pk_add_f32 v[252:253], v[74:75], v[252:253]
	v_pk_add_f32 v[252:253], v[76:77], v[252:253]
	v_pk_add_f32 v[252:253], v[78:79], v[252:253]
	v_cvt_pk_bf16_f32 v124, v64, v65
	v_cvt_pk_bf16_f32 v125, v66, v67
	v_cvt_pk_bf16_f32 v126, v68, v69
	v_cvt_pk_bf16_f32 v127, v70, v71
	v_cvt_pk_bf16_f32 v80, v72, v73
	v_cvt_pk_bf16_f32 v81, v74, v75
	v_cvt_pk_bf16_f32 v82, v76, v77
	v_cvt_pk_bf16_f32 v83, v78, v79
	v_add_f32_e32 v252, v252, v253
	v_add_f32_e32 v175, v175, v252
	v_mfma_f32_32x32x16_bf16 v[48:63], v[228:231], v[124:127], v[48:63]
	v_mfma_f32_32x32x16_bf16 v[32:47], v[232:235], v[124:127], v[32:47]
	v_mfma_f32_32x32x16_bf16 v[48:63], v[236:239], v[80:83], v[48:63]
	v_mfma_f32_32x32x16_bf16 v[32:47], v[240:243], v[80:83], v[32:47]
